# one static s_setprio 1 at kernel entry for waves 0-3 (leading half), all 120 per-block priority flips deleted
# speedup vs baseline: 1.0067x; 1.0065x over previous
_Z14fwd_megakernel6Params:
	s_mov_b64 s[92:93], s[0:1]
	v_readfirstlane_b32 s3, v0
	s_nop 3
	s_bfe_u32 s3, s3, 0x40006
	s_cmp_lt_u32 s3, 4
	s_cbranch_scc0 .Lprio_done
	s_setprio 1
